# v38 + mixer-A q/k rope of the light prep items staged through LDS (coalesced 1 KB-per-instruction global loads/stores instead of 16 B per lane at 64-B stride)
# baseline (speedup 1.0000x reference)
; __device__ __forceinline__ unsigned pk2(float lo, float hi) { f32x2_t v = {lo, hi}; bf16x2_t b = __builtin_convertvector(v, bf16x2_t); return __builtin_bit_cast(unsigned, b); }
; __device__ __forceinline__ void phase_prep(const Params& P, int l, unsigned char* lds) {
;     ...
; #pragma unroll 1
;             for (int rep = 0; rep < 2; ++rep) {
;                 const int id = tid + 512 * rep, tok = id >> 4, vv = id & 15; const bool isq = vv < 8;
;                 if (is_ctx && !isq) continue;
;                 bf16_t* p = proj + (size_t)(r0 + tok) * INW + (isq ? PA_Q + 32 * vv : PA_K + 32 * (vv - 8));
;                 u32x4 w[4]; float v[32];
; #pragma unroll
;                 for (int j = 0; j < 4; ++j) { w[j] = *((const u32x4*)p + j);
;                     v[8 * j + 0] = bflo(w[j].x); v[8 * j + 1] = bfhi(w[j].x); v[8 * j + 2] = bflo(w[j].y); v[8 * j + 3] = bfhi(w[j].y);
;                     v[8 * j + 4] = bflo(w[j].z); v[8 * j + 5] = bfhi(w[j].z); v[8 * j + 6] = bflo(w[j].w); v[8 * j + 7] = bfhi(w[j].w); }
;                 if (!is_ctx) { const int tl = t0 - CTX + tok; rope_half<8>(v, tl >> 6); rope_half<8>(v + 16, tl & 63); }
;                 const float sc = isq ? 0.17677669529663687f * LOG2E : 1.0f;
; #pragma unroll
;                 for (int j = 0; j < 4; ++j) { u32x4 o; o.x = pk2(v[8 * j] * sc, v[8 * j + 1] * sc); o.y = pk2(v[8 * j + 2] * sc, v[8 * j + 3] * sc); o.z = pk2(v[8 * j + 4] * sc, v[8 * j + 5] * sc); o.w = pk2(v[8 * j + 6] * sc, v[8 * j + 7] * sc);
;                     *((u32x4*)p + j) = o; }
;             }
.LBB0_277:
	s_and_b64 vcc, exec, s[38:39]
	s_cbranch_vccz .LBB0_227
	v_mov_b32_e32 v84, v44
	v_lshrrev_b32_e32 v86, 6, v84
	v_add_u32_e32 v86, s29, v86
	v_mul_u32_u24_e32 v86, 0x1600, v86
	v_and_b32_e32 v85, 63, v84
	v_lshl_add_u32 v85, v85, 4, v86
	global_load_dwordx4 v[52:55], v85, s[10:11]
	v_add_u32_e32 v84, 512, v44
	v_lshrrev_b32_e32 v86, 6, v84
	v_add_u32_e32 v86, s29, v86
	v_mul_u32_u24_e32 v86, 0x1600, v86
	v_and_b32_e32 v85, 63, v84
	v_lshl_add_u32 v85, v85, 4, v86
	global_load_dwordx4 v[56:59], v85, s[10:11]
	v_add_u32_e32 v84, 1024, v44
	v_lshrrev_b32_e32 v86, 6, v84
	v_add_u32_e32 v86, s29, v86
	v_mul_u32_u24_e32 v86, 0x1600, v86
	v_and_b32_e32 v85, 63, v84
	v_lshl_add_u32 v85, v85, 4, v86
	global_load_dwordx4 v[60:63], v85, s[10:11]
	v_add_u32_e32 v84, 1536, v44
	v_lshrrev_b32_e32 v86, 6, v84
	v_add_u32_e32 v86, s29, v86
	v_mul_u32_u24_e32 v86, 0x1600, v86
	v_and_b32_e32 v85, 63, v84
	v_lshl_add_u32 v85, v85, 4, v86
	global_load_dwordx4 v[64:67], v85, s[10:11]
	v_add_u32_e32 v84, 2048, v44
	v_lshrrev_b32_e32 v86, 6, v84
	v_add_u32_e32 v86, s29, v86
	v_mul_u32_u24_e32 v86, 0x1600, v86
	v_and_b32_e32 v85, 63, v84
	v_lshl_add_u32 v85, v85, 4, v86
	global_load_dwordx4 v[68:71], v85, s[10:11]
	v_add_u32_e32 v84, 2560, v44
	v_lshrrev_b32_e32 v86, 6, v84
	v_add_u32_e32 v86, s29, v86
	v_mul_u32_u24_e32 v86, 0x1600, v86
	v_and_b32_e32 v85, 63, v84
	v_lshl_add_u32 v85, v85, 4, v86
	global_load_dwordx4 v[72:75], v85, s[10:11]
	v_add_u32_e32 v84, 3072, v44
	v_lshrrev_b32_e32 v86, 6, v84
	v_add_u32_e32 v86, s29, v86
	v_mul_u32_u24_e32 v86, 0x1600, v86
	v_and_b32_e32 v85, 63, v84
	v_lshl_add_u32 v85, v85, 4, v86
	global_load_dwordx4 v[76:79], v85, s[10:11]
	v_add_u32_e32 v84, 3584, v44
	v_lshrrev_b32_e32 v86, 6, v84
	v_add_u32_e32 v86, s29, v86
	v_mul_u32_u24_e32 v86, 0x1600, v86
	v_and_b32_e32 v85, 63, v84
	v_lshl_add_u32 v85, v85, 4, v86
	global_load_dwordx4 v[80:83], v85, s[10:11]
	v_mov_b32_e32 v84, v44
	v_lshlrev_b32_e32 v87, 4, v84
	s_waitcnt vmcnt(7)
	ds_write_b128 v87, v[52:55]
	v_add_u32_e32 v84, 512, v44
	v_lshlrev_b32_e32 v87, 4, v84
	s_waitcnt vmcnt(6)
	ds_write_b128 v87, v[56:59]
	v_add_u32_e32 v84, 1024, v44
	v_lshlrev_b32_e32 v87, 4, v84
	s_waitcnt vmcnt(5)
	ds_write_b128 v87, v[60:63]
	v_add_u32_e32 v84, 1536, v44
	v_lshlrev_b32_e32 v87, 4, v84
	s_waitcnt vmcnt(4)
	ds_write_b128 v87, v[64:67]
	v_add_u32_e32 v84, 2048, v44
	v_lshlrev_b32_e32 v87, 4, v84
	s_waitcnt vmcnt(3)
	ds_write_b128 v87, v[68:71]
	v_add_u32_e32 v84, 2560, v44
	v_lshlrev_b32_e32 v87, 4, v84
	s_waitcnt vmcnt(2)
	ds_write_b128 v87, v[72:75]
	v_add_u32_e32 v84, 3072, v44
	v_lshlrev_b32_e32 v87, 4, v84
	s_waitcnt vmcnt(1)
	ds_write_b128 v87, v[76:79]
	v_add_u32_e32 v84, 3584, v44
	v_lshlrev_b32_e32 v87, 4, v84
	s_waitcnt vmcnt(0)
	ds_write_b128 v87, v[80:83]
	s_waitcnt lgkmcnt(0)
	s_barrier
	v_and_b32_e32 v1, 15, v44
	v_cmp_gt_u32_e32 vcc, 8, v1
	v_mov_b32_e32 v0, 0x3e8293ee
	v_lshlrev_b32_e32 v128, 6, v1
	v_cndmask_b32_e32 v0, 1.0, v0, vcc
	s_or_b64 s[38:39], s[42:43], vcc
	v_lshl_add_u64 v[2:3], s[10:11], 0, v[128:129]
	s_add_i32 s15, s64, 0xffffff00
	v_mov_b32_e32 v1, v0
	s_mov_b32 s12, 0
	s_mov_b64 s[40:41], -1
	s_branch .LBB0_281
.LBB0_279:
	v_pk_mul_f32 v[14:15], v[0:1], v[14:15]
	v_pk_mul_f32 v[16:17], v[0:1], v[16:17]
	v_pk_mov_b32 v[14:15], v[14:15], v[14:15] op_sel:[1,0]
	v_pk_mov_b32 v[16:17], v[16:17], v[16:17] op_sel:[1,0]
	v_cvt_pk_bf16_f32 v14, v14, v15
	v_cvt_pk_bf16_f32 v15, v16, v17
	v_pk_mul_f32 v[16:17], v[0:1], v[18:19]
	v_pk_mul_f32 v[18:19], v[0:1], v[20:21]
	v_pk_mov_b32 v[16:17], v[16:17], v[16:17] op_sel:[1,0]
	v_pk_mov_b32 v[18:19], v[18:19], v[18:19] op_sel:[1,0]
	v_cvt_pk_bf16_f32 v16, v16, v17
	v_cvt_pk_bf16_f32 v17, v18, v19
	v_pk_mul_f32 v[36:37], v[0:1], v[36:37]
	v_pk_mul_f32 v[34:35], v[0:1], v[34:35]
	v_pk_mul_f32 v[32:33], v[0:1], v[32:33]
	v_pk_mul_f32 v[30:31], v[0:1], v[30:31]
	ds_write_b128 v51, v[14:17] offset:16
	v_pk_mul_f32 v[6:7], v[0:1], v[6:7]
	v_pk_mul_f32 v[8:9], v[0:1], v[8:9]
	v_pk_mul_f32 v[14:15], v[0:1], v[28:29]
	v_pk_mul_f32 v[16:17], v[0:1], v[26:27]
	v_pk_mov_b32 v[36:37], v[36:37], v[36:37] op_sel:[1,0]
	v_pk_mov_b32 v[34:35], v[34:35], v[34:35] op_sel:[1,0]
	v_pk_mov_b32 v[32:33], v[32:33], v[32:33] op_sel:[1,0]
	v_pk_mov_b32 v[30:31], v[30:31], v[30:31] op_sel:[1,0]
	v_cvt_pk_bf16_f32 v14, v14, v15
	v_cvt_pk_bf16_f32 v15, v16, v17
	v_pk_mul_f32 v[16:17], v[0:1], v[24:25]
	v_pk_mul_f32 v[18:19], v[0:1], v[22:23]
	v_cvt_pk_bf16_f32 v6, v6, v7
	v_cvt_pk_bf16_f32 v7, v8, v9
	v_pk_mul_f32 v[8:9], v[0:1], v[10:11]
	v_pk_mul_f32 v[10:11], v[0:1], v[12:13]
	v_cvt_pk_bf16_f32 v36, v36, v37
	v_cvt_pk_bf16_f32 v37, v34, v35
	v_cvt_pk_bf16_f32 v38, v32, v33
	v_cvt_pk_bf16_f32 v39, v30, v31
	v_cvt_pk_bf16_f32 v16, v16, v17
	v_cvt_pk_bf16_f32 v17, v18, v19
	v_cvt_pk_bf16_f32 v8, v8, v9
	v_cvt_pk_bf16_f32 v9, v10, v11
	ds_write_b128 v51, v[36:39]
	ds_write_b128 v51, v[14:17] offset:32
	ds_write_b128 v51, v[6:9] offset:48

; template <int NF> __device__ __forceinline__ void rope_half(float* v, int pos) {
; #pragma unroll
;     for (int i = 0; i < NF; ++i) {
;         const float inv_freq = exp2f(-13.287712379549449f * (float)i / (float)NF);
;         const float rev = (float)pos * inv_freq * 0.15915494309189535f;
;         const float cs = __builtin_amdgcn_cosf(rev), sn = __builtin_amdgcn_sinf(rev);
;         const float x1 = v[i], x2 = v[NF + i];
;         v[i] = x1 * cs - x2 * sn; v[NF + i] = x2 * cs + x1 * sn;
;     }
; __device__ __forceinline__ void phase_prep(const Params& P, int l, unsigned char* lds) {
;     ...
;                 const int id = tid + 512 * rep, tok = id >> 4, vv = id & 15; const bool isq = vv < 8;
;                 if (is_ctx && !isq) continue;
;                 bf16_t* p = proj + (size_t)(r0 + tok) * INW + (isq ? PA_Q + 32 * vv : PA_K + 32 * (vv - 8));
;                 u32x4 w[4]; float v[32];
; #pragma unroll
;                 for (int j = 0; j < 4; ++j) { w[j] = *((const u32x4*)p + j);
;                     v[8 * j + 0] = bflo(w[j].x); v[8 * j + 1] = bfhi(w[j].x); v[8 * j + 2] = bflo(w[j].y); v[8 * j + 3] = bfhi(w[j].y);
;                     v[8 * j + 4] = bflo(w[j].z); v[8 * j + 5] = bfhi(w[j].z); v[8 * j + 6] = bflo(w[j].w); v[8 * j + 7] = bfhi(w[j].w); }
;                 if (!is_ctx) { const int tl = t0 - CTX + tok; rope_half<8>(v, tl >> 6); rope_half<8>(v + 16, tl & 63); }
.LBB0_281:
	s_and_saveexec_b64 s[48:49], s[38:39]
	s_cbranch_execz .LBB0_280
	v_add_u32_e32 v4, s12, v44
	v_ashrrev_i32_e32 v38, 4, v4
	v_and_b32_e32 v51, 15, v44
	v_lshlrev_b32_e32 v51, 6, v51
	v_lshl_add_u32 v51, v38, 10, v51
	v_add_u32_e32 v4, s29, v38
	v_mad_i64_i32 v[4:5], s[12:13], v4, s23, v[2:3]
	ds_read_b128 v[6:9], v51
	ds_read_b128 v[10:13], v51 offset:16
	ds_read_b128 v[40:43], v51 offset:32
	ds_read_b128 v[46:49], v51 offset:48
	s_andn2_b64 vcc, exec, s[42:43]
	s_waitcnt lgkmcnt(3)
	v_and_b32_e32 v36, 0xffff0000, v6
	v_lshlrev_b32_e32 v37, 16, v6
	s_waitcnt lgkmcnt(2)
	v_and_b32_e32 v14, 0xffff0000, v10
	v_lshlrev_b32_e32 v15, 16, v10
	v_and_b32_e32 v34, 0xffff0000, v7
	v_lshlrev_b32_e32 v35, 16, v7
	v_and_b32_e32 v16, 0xffff0000, v11
	v_lshlrev_b32_e32 v17, 16, v11
	v_and_b32_e32 v32, 0xffff0000, v8
	v_lshlrev_b32_e32 v33, 16, v8
	v_and_b32_e32 v18, 0xffff0000, v12
	v_lshlrev_b32_e32 v19, 16, v12
	v_and_b32_e32 v30, 0xffff0000, v9
	v_lshlrev_b32_e32 v31, 16, v9
	v_and_b32_e32 v20, 0xffff0000, v13
	v_lshlrev_b32_e32 v21, 16, v13
	s_waitcnt lgkmcnt(1)
	v_lshlrev_b32_e32 v28, 16, v40
	v_and_b32_e32 v29, 0xffff0000, v40
	s_waitcnt lgkmcnt(0)
	v_lshlrev_b32_e32 v6, 16, v46
	v_and_b32_e32 v7, 0xffff0000, v46
	v_lshlrev_b32_e32 v26, 16, v41
	v_and_b32_e32 v27, 0xffff0000, v41
	v_lshlrev_b32_e32 v8, 16, v47
	v_and_b32_e32 v9, 0xffff0000, v47
	v_lshlrev_b32_e32 v24, 16, v42
	v_and_b32_e32 v25, 0xffff0000, v42
	v_lshlrev_b32_e32 v10, 16, v48
	v_and_b32_e32 v11, 0xffff0000, v48
	v_lshlrev_b32_e32 v22, 16, v43
	v_and_b32_e32 v23, 0xffff0000, v43
	v_lshlrev_b32_e32 v12, 16, v49
	v_and_b32_e32 v13, 0xffff0000, v49
	s_cbranch_vccnz .LBB0_279
	v_add_u32_e32 v45, s15, v38
	v_ashrrev_i32_e32 v38, 6, v45
	v_cvt_f32_i32_e32 v50, v38
	v_mul_f32_e32 v38, 0.15915494, v50
	v_mul_f32_e32 v40, 0x3ea1e89b, v50
	v_cos_f32_e32 v39, v38
	v_sin_f32_e32 v41, v38
	v_mul_f32_e32 v38, 0.15915494, v40
	v_sin_f32_e32 v40, v38
	v_cos_f32_e32 v38, v38
	v_mul_f32_e32 v42, 0x3dcccccd, v50
	v_mul_f32_e32 v46, 0.15915494, v42
	v_pk_mul_f32 v[42:43], v[40:41], v[14:15]
	v_pk_mul_f32 v[14:15], v[38:39], v[14:15]
	v_pk_fma_f32 v[42:43], v[38:39], v[36:37], v[42:43] neg_lo:[0,0,1] neg_hi:[0,0,1]
	v_mul_f32_e32 v38, 0x3c23d70b, v50
	v_cos_f32_e32 v47, v46
	v_sin_f32_e32 v49, v46
	v_mul_f32_e32 v46, 0x3d0186e3, v50
	v_mul_f32_e32 v38, 0.15915494, v38
	v_mul_f32_e32 v46, 0.15915494, v46
	v_pk_fma_f32 v[14:15], v[40:41], v[36:37], v[14:15]
	v_cos_f32_e32 v39, v38
	v_sin_f32_e32 v41, v38
	v_mul_f32_e32 v38, 0x3b4f3e39, v50
	v_sin_f32_e32 v48, v46
	v_cos_f32_e32 v46, v46
	v_mul_f32_e32 v38, 0.15915494, v38
	v_sin_f32_e32 v40, v38
	v_cos_f32_e32 v38, v38
	v_pk_mul_f32 v[36:37], v[48:49], v[16:17]
	v_pk_mul_f32 v[16:17], v[46:47], v[16:17]
	v_pk_fma_f32 v[36:37], v[46:47], v[34:35], v[36:37] neg_lo:[0,0,1] neg_hi:[0,0,1]
	v_pk_fma_f32 v[16:17], v[48:49], v[34:35], v[16:17]
	v_pk_mul_f32 v[34:35], v[40:41], v[18:19]
	v_mul_f32_e32 v46, 0x3a831270, v50
	v_pk_fma_f32 v[34:35], v[38:39], v[32:33], v[34:35] neg_lo:[0,0,1] neg_hi:[0,0,1]
	v_pk_mul_f32 v[18:19], v[38:39], v[18:19]
	v_and_b32_e32 v38, 63, v45
	v_mul_f32_e32 v46, 0.15915494, v46
	v_cvt_f32_ubyte0_e32 v45, v38
	v_cos_f32_e32 v47, v46
	v_sin_f32_e32 v49, v46
	v_mul_f32_e32 v46, 0x39a5cb61, v50
	v_mul_f32_e32 v39, 0.15915494, v45
	v_mul_f32_e32 v46, 0.15915494, v46
	v_pk_fma_f32 v[18:19], v[40:41], v[32:33], v[18:19]
	v_cos_f32_e32 v38, v39
	v_sin_f32_e32 v40, v39
	v_mul_f32_e32 v39, 0x3ea1e89b, v45
	v_sin_f32_e32 v48, v46
	v_cos_f32_e32 v46, v46
	v_mul_f32_e32 v39, 0.15915494, v39
	v_sin_f32_e32 v41, v39
	v_cos_f32_e32 v39, v39
	v_pk_mul_f32 v[32:33], v[48:49], v[20:21]
	v_pk_mul_f32 v[20:21], v[46:47], v[20:21]
	v_pk_fma_f32 v[32:33], v[46:47], v[30:31], v[32:33] neg_lo:[0,0,1] neg_hi:[0,0,1]
	v_pk_fma_f32 v[20:21], v[48:49], v[30:31], v[20:21]
	v_pk_mul_f32 v[30:31], v[40:41], v[6:7]
	v_pk_mul_f32 v[6:7], v[38:39], v[6:7]
	v_pk_fma_f32 v[46:47], v[38:39], v[28:29], v[30:31] neg_lo:[0,0,1] neg_hi:[0,0,1]
	v_mul_f32_e32 v30, 0x3dcccccd, v45
	v_mul_f32_e32 v31, 0.15915494, v30
	v_cos_f32_e32 v30, v31
	v_sin_f32_e32 v48, v31
	v_mul_f32_e32 v31, 0x3d0186e3, v45
	v_mul_f32_e32 v31, 0.15915494, v31
	v_sin_f32_e32 v49, v31
	v_cos_f32_e32 v31, v31
	v_pk_fma_f32 v[6:7], v[40:41], v[28:29], v[6:7]
	v_pk_mul_f32 v[28:29], v[48:49], v[8:9]
	s_nop 0
	v_pk_fma_f32 v[38:39], v[30:31], v[26:27], v[28:29] neg_lo:[0,0,1] neg_hi:[0,0,1]
	v_mul_f32_e32 v28, 0x3c23d70b, v45
	v_mul_f32_e32 v29, 0.15915494, v28
	v_cos_f32_e32 v28, v29
	v_sin_f32_e32 v40, v29
	v_mul_f32_e32 v29, 0x3b4f3e39, v45
	v_mul_f32_e32 v29, 0.15915494, v29
	v_sin_f32_e32 v41, v29
	v_cos_f32_e32 v29, v29
	v_pk_mul_f32 v[8:9], v[30:31], v[8:9]
	s_nop 0
	v_pk_fma_f32 v[8:9], v[48:49], v[26:27], v[8:9]
	v_pk_mul_f32 v[26:27], v[40:41], v[10:11]
	v_pk_mul_f32 v[10:11], v[28:29], v[10:11]
	v_pk_fma_f32 v[48:49], v[28:29], v[24:25], v[26:27] neg_lo:[0,0,1] neg_hi:[0,0,1]
	v_mul_f32_e32 v26, 0x3a831270, v45
	v_mul_f32_e32 v27, 0.15915494, v26
	v_cos_f32_e32 v26, v27
	v_sin_f32_e32 v30, v27
	v_mul_f32_e32 v27, 0x39a5cb61, v45
	v_mul_f32_e32 v27, 0.15915494, v27
	v_sin_f32_e32 v31, v27
	v_cos_f32_e32 v27, v27
	v_pk_fma_f32 v[10:11], v[40:41], v[24:25], v[10:11]
	v_mov_b64_e32 v[28:29], v[46:47]
	v_pk_mul_f32 v[24:25], v[30:31], v[12:13]
	v_pk_mul_f32 v[12:13], v[26:27], v[12:13]
	v_pk_fma_f32 v[40:41], v[26:27], v[22:23], v[24:25] neg_lo:[0,0,1] neg_hi:[0,0,1]
	v_pk_fma_f32 v[12:13], v[30:31], v[22:23], v[12:13]
	v_mov_b64_e32 v[30:31], v[32:33]
	v_mov_b64_e32 v[32:33], v[34:35]
	v_mov_b64_e32 v[34:35], v[36:37]
	v_mov_b64_e32 v[36:37], v[42:43]
	v_mov_b64_e32 v[26:27], v[38:39]
	v_mov_b64_e32 v[24:25], v[48:49]
	v_mov_b64_e32 v[22:23], v[40:41]
	s_branch .LBB0_279
; __device__ __forceinline__ void phase_prep(const Params& P, int l, unsigned char* lds) {
;     ...
;             if (tid < 384) {
;                 const int tok = tid / 6, vv = tid - tok * 6; const bool isq = vv < 4;
;                 bf16_t* p = proj + (size_t)(r0 + tok) * INW + (isq ? PC_Q + 64 * vv : PC_K + 64 * (vv - 4));
;                 const float* gain = (isq ? P.q_norm : P.k_norm) + (size_t)l * 64;
;                 float v[64]; float s2 = 0.f;
; #pragma unroll
;                 for (int j = 0; j < 8; ++j) { const u32x4 w = *((const u32x4*)p + j);
;                     v[8 * j + 0] = bflo(w.x); v[8 * j + 1] = bfhi(w.x); v[8 * j + 2] = bflo(w.y); v[8 * j + 3] = bfhi(w.y);
;                     v[8 * j + 4] = bflo(w.z); v[8 * j + 5] = bfhi(w.z); v[8 * j + 6] = bflo(w.w); v[8 * j + 7] = bfhi(w.w); }
; #pragma unroll
;                 for (int j = 0; j < 64; ++j) s2 += v[j] * v[j];
.LBB0_284:
	s_waitcnt lgkmcnt(0)
	s_barrier
	v_mov_b32_e32 v84, v44
	v_lshlrev_b32_e32 v87, 4, v84
	ds_read_b128 v[52:55], v87
	v_add_u32_e32 v84, 512, v44
	v_lshlrev_b32_e32 v87, 4, v84
	ds_read_b128 v[56:59], v87
	v_add_u32_e32 v84, 1024, v44
	v_lshlrev_b32_e32 v87, 4, v84
	ds_read_b128 v[60:63], v87
	v_add_u32_e32 v84, 1536, v44
	v_lshlrev_b32_e32 v87, 4, v84
	ds_read_b128 v[64:67], v87
	v_add_u32_e32 v84, 2048, v44
	v_lshlrev_b32_e32 v87, 4, v84
	ds_read_b128 v[68:71], v87
	v_add_u32_e32 v84, 2560, v44
	v_lshlrev_b32_e32 v87, 4, v84
	ds_read_b128 v[72:75], v87
	v_add_u32_e32 v84, 3072, v44
	v_lshlrev_b32_e32 v87, 4, v84
	ds_read_b128 v[76:79], v87
	v_add_u32_e32 v84, 3584, v44
	v_lshlrev_b32_e32 v87, 4, v84
	ds_read_b128 v[80:83], v87
	v_mov_b32_e32 v84, v44
	v_lshrrev_b32_e32 v86, 6, v84
	v_add_u32_e32 v86, s29, v86
	v_mul_u32_u24_e32 v86, 0x1600, v86
	v_and_b32_e32 v85, 63, v84
	v_lshl_add_u32 v85, v85, 4, v86
	s_waitcnt lgkmcnt(7)
	global_store_dwordx4 v85, v[52:55], s[10:11]
	v_add_u32_e32 v84, 512, v44
	v_lshrrev_b32_e32 v86, 6, v84
	v_add_u32_e32 v86, s29, v86
	v_mul_u32_u24_e32 v86, 0x1600, v86
	v_and_b32_e32 v85, 63, v84
	v_lshl_add_u32 v85, v85, 4, v86
	s_waitcnt lgkmcnt(6)
	global_store_dwordx4 v85, v[56:59], s[10:11]
	v_add_u32_e32 v84, 1024, v44
	v_lshrrev_b32_e32 v86, 6, v84
	v_add_u32_e32 v86, s29, v86
	v_mul_u32_u24_e32 v86, 0x1600, v86
	v_and_b32_e32 v85, 63, v84
	v_lshl_add_u32 v85, v85, 4, v86
	s_waitcnt lgkmcnt(5)
	global_store_dwordx4 v85, v[60:63], s[10:11]
	v_add_u32_e32 v84, 1536, v44
	v_lshrrev_b32_e32 v86, 6, v84
	v_add_u32_e32 v86, s29, v86
	v_mul_u32_u24_e32 v86, 0x1600, v86
	v_and_b32_e32 v85, 63, v84
	v_lshl_add_u32 v85, v85, 4, v86
	s_waitcnt lgkmcnt(4)
	global_store_dwordx4 v85, v[64:67], s[10:11]
	v_add_u32_e32 v84, 2048, v44
	v_lshrrev_b32_e32 v86, 6, v84
	v_add_u32_e32 v86, s29, v86
	v_mul_u32_u24_e32 v86, 0x1600, v86
	v_and_b32_e32 v85, 63, v84
	v_lshl_add_u32 v85, v85, 4, v86
	s_waitcnt lgkmcnt(3)
	global_store_dwordx4 v85, v[68:71], s[10:11]
	v_add_u32_e32 v84, 2560, v44
	v_lshrrev_b32_e32 v86, 6, v84
	v_add_u32_e32 v86, s29, v86
	v_mul_u32_u24_e32 v86, 0x1600, v86
	v_and_b32_e32 v85, 63, v84
	v_lshl_add_u32 v85, v85, 4, v86
	s_waitcnt lgkmcnt(2)
	global_store_dwordx4 v85, v[72:75], s[10:11]
	v_add_u32_e32 v84, 3072, v44
	v_lshrrev_b32_e32 v86, 6, v84
	v_add_u32_e32 v86, s29, v86
	v_mul_u32_u24_e32 v86, 0x1600, v86
	v_and_b32_e32 v85, 63, v84
	v_lshl_add_u32 v85, v85, 4, v86
	s_waitcnt lgkmcnt(1)
	global_store_dwordx4 v85, v[76:79], s[10:11]
	v_add_u32_e32 v84, 3584, v44
	v_lshrrev_b32_e32 v86, 6, v84
	v_add_u32_e32 v86, s29, v86
	v_mul_u32_u24_e32 v86, 0x1600, v86
	v_and_b32_e32 v85, 63, v84
	v_lshl_add_u32 v85, v85, 4, v86
	s_waitcnt lgkmcnt(0)
	global_store_dwordx4 v85, v[80:83], s[10:11]
	s_barrier
	s_movk_i32 s12, 0x180
	v_cmp_gt_i32_e32 vcc, s12, v44
	s_and_saveexec_b64 s[48:49], vcc
	s_cbranch_execz .LBB0_288
	v_mul_hi_i32 v0, v44, s26
	v_lshrrev_b32_e32 v1, 31, v0
	v_add_u32_e32 v45, v0, v1
	v_mad_u64_u32 v[0:1], s[12:13], v45, -6, v[44:45]
	v_add_u32_e32 v1, s29, v45
	v_mov_b64_e32 v[2:3], s[10:11]
	v_mad_i64_i32 v[2:3], s[12:13], v1, s23, v[2:3]
	v_mov_b32_e32 v1, 0x800
	v_lshl_add_u32 v4, v0, 6, v1
	v_ashrrev_i32_e32 v5, 31, v4
	v_lshl_add_u64 v[46:47], v[4:5], 1, v[2:3]
	global_load_dwordx4 v[16:19], v[46:47], off offset:80
	global_load_dwordx4 v[20:23], v[46:47], off offset:112
	global_load_dwordx4 v[24:27], v[46:47], off offset:64
	global_load_dwordx4 v[28:31], v[46:47], off offset:96
	global_load_dwordx4 v[32:35], v[46:47], off offset:16
	global_load_dwordx4 v[36:39], v[46:47], off offset:48
	global_load_dwordx4 v[12:15], v[46:47], off
	global_load_dwordx4 v[8:11], v[46:47], off offset:32
	v_mov_b32_e32 v1, s47
	v_mov_b32_e32 v2, s45
	v_mov_b32_e32 v3, s46
	v_mov_b32_e32 v4, s44
	v_cmp_gt_i32_e64 s[38:39], 4, v0
	s_waitcnt vmcnt(7)
	v_and_b32_e32 v71, 0xffff0000, v17
	s_waitcnt vmcnt(6)
	v_and_b32_e32 v61, 0xffff0000, v21
	v_lshlrev_b32_e32 v60, 16, v21
	v_and_b32_e32 v65, 0xffff0000, v20
	s_waitcnt vmcnt(3)
	v_and_b32_e32 v105, 0xffff0000, v32
	v_lshlrev_b32_e32 v104, 16, v32
	s_waitcnt vmcnt(1)
	v_and_b32_e32 v113, 0xffff0000, v12
	v_lshlrev_b32_e32 v112, 16, v12
	s_waitcnt vmcnt(0)
	v_and_b32_e32 v101, 0xffff0000, v11
	v_lshlrev_b32_e32 v100, 16, v11
	v_and_b32_e32 v51, 0xffff0000, v10
	v_lshlrev_b32_e32 v50, 16, v10
	v_and_b32_e32 v111, 0xffff0000, v13
	v_lshlrev_b32_e32 v110, 16, v13
	v_pk_mul_f32 v[10:11], v[112:113], v[112:113]
	v_and_b32_e32 v53, 0xffff0000, v9
	v_lshlrev_b32_e32 v52, 16, v9
	v_and_b32_e32 v55, 0xffff0000, v8
	v_lshlrev_b32_e32 v54, 16, v8
	v_pk_mul_f32 v[8:9], v[110:111], v[110:111]
	v_add_f32_e32 v10, v10, v11
	v_and_b32_e32 v109, 0xffff0000, v14
	v_lshlrev_b32_e32 v108, 16, v14
	v_add_f32_e32 v8, v8, v10
	v_add_f32_e32 v10, v9, v8
	v_pk_mul_f32 v[8:9], v[108:109], v[108:109]
	v_and_b32_e32 v107, 0xffff0000, v15
	v_lshlrev_b32_e32 v106, 16, v15
	v_add_f32_e32 v8, v8, v10
	v_add_f32_e32 v10, v9, v8
	v_pk_mul_f32 v[8:9], v[106:107], v[106:107]
	v_and_b32_e32 v103, 0xffff0000, v33
	v_add_f32_e32 v8, v8, v10
	v_add_f32_e32 v10, v9, v8
	v_pk_mul_f32 v[8:9], v[104:105], v[104:105]
	v_lshlrev_b32_e32 v102, 16, v33
	v_add_f32_e32 v8, v8, v10
	v_add_f32_e32 v10, v9, v8
	v_pk_mul_f32 v[8:9], v[102:103], v[102:103]
	v_and_b32_e32 v99, 0xffff0000, v34
	v_lshlrev_b32_e32 v98, 16, v34
	v_add_f32_e32 v8, v8, v10
	v_lshlrev_b32_e32 v64, 16, v20
	v_pk_mul_f32 v[20:21], v[98:99], v[98:99]
	v_add_f32_e32 v10, v9, v8
	v_cndmask_b32_e64 v1, v1, v2, s[38:39]
	v_cndmask_b32_e64 v0, v3, v4, s[38:39]
	v_and_b32_e32 v93, 0xffff0000, v35
	v_lshlrev_b32_e32 v92, 16, v35
; __device__ __forceinline__ void phase_prep(const Params& P, int l, unsigned char* lds) {
;     ...
;                 float v[64]; float s2 = 0.f;
; #pragma unroll
;                 for (int j = 0; j < 8; ++j) { const u32x4 w = *((const u32x4*)p + j);
;                     v[8 * j + 0] = bflo(w.x); v[8 * j + 1] = bfhi(w.x); v[8 * j + 2] = bflo(w.y); v[8 * j + 3] = bfhi(w.y);
;                     v[8 * j + 4] = bflo(w.z); v[8 * j + 5] = bfhi(w.z); v[8 * j + 6] = bflo(w.w); v[8 * j + 7] = bfhi(w.w); }
; #pragma unroll
;                 for (int j = 0; j < 64; ++j) s2 += v[j] * v[j];
;                 const float rstd = 1.0f / sqrtf(s2 * (1.0f / 64.0f) + RMS_EPS);
	v_add_f32_e32 v10, v20, v10
	v_lshl_add_u64 v[48:49], v[0:1], 0, s[24:25]
	v_lshlrev_b32_e32 v70, 16, v17
	v_and_b32_e32 v75, 0xffff0000, v16
	v_lshlrev_b32_e32 v74, 16, v16
	v_pk_mul_f32 v[16:17], v[92:93], v[92:93]
	v_add_f32_e32 v12, v21, v10
	global_load_dwordx4 v[0:3], v[48:49], off offset:16
	global_load_dwordx4 v[4:7], v[48:49], off
	v_add_f32_e32 v12, v16, v12
	v_add_f32_e32 v14, v17, v12
	v_pk_mul_f32 v[12:13], v[54:55], v[54:55]
	v_and_b32_e32 v97, 0xffff0000, v36
	v_add_f32_e32 v12, v12, v14
	v_add_f32_e32 v14, v13, v12
	v_pk_mul_f32 v[12:13], v[52:53], v[52:53]
	v_lshlrev_b32_e32 v96, 16, v36
	v_add_f32_e32 v12, v12, v14
	v_add_f32_e32 v14, v13, v12
	v_pk_mul_f32 v[12:13], v[50:51], v[50:51]
	v_and_b32_e32 v95, 0xffff0000, v37
	v_add_f32_e32 v12, v12, v14
	v_add_f32_e32 v14, v13, v12
	v_pk_mul_f32 v[12:13], v[100:101], v[100:101]
	v_lshlrev_b32_e32 v94, 16, v37
	v_add_f32_e32 v12, v12, v14
	v_add_f32_e32 v14, v13, v12
	v_pk_mul_f32 v[12:13], v[96:97], v[96:97]
	v_pk_mul_f32 v[10:11], v[94:95], v[94:95]
	v_add_f32_e32 v12, v12, v14
	v_add_f32_e32 v12, v13, v12
	v_and_b32_e32 v91, 0xffff0000, v38
	v_lshlrev_b32_e32 v90, 16, v38
	v_add_f32_e32 v10, v10, v12
	v_pk_mul_f32 v[8:9], v[90:91], v[90:91]
	v_add_f32_e32 v10, v11, v10
	v_and_b32_e32 v89, 0xffff0000, v39
	v_lshlrev_b32_e32 v88, 16, v39
	v_add_f32_e32 v8, v8, v10
	v_and_b32_e32 v63, 0xffff0000, v19
	v_lshlrev_b32_e32 v62, 16, v19
	v_and_b32_e32 v67, 0xffff0000, v18
	v_lshlrev_b32_e32 v66, 16, v18
	v_pk_mul_f32 v[18:19], v[88:89], v[88:89]
	v_add_f32_e32 v8, v9, v8
	v_and_b32_e32 v87, 0xffff0000, v24
	v_lshlrev_b32_e32 v86, 16, v24
	v_add_f32_e32 v8, v18, v8
	v_pk_mul_f32 v[126:127], v[86:87], v[86:87]
	v_add_f32_e32 v8, v19, v8
	v_and_b32_e32 v85, 0xffff0000, v25
	v_lshlrev_b32_e32 v84, 16, v25
	v_add_f32_e32 v8, v126, v8
	v_pk_mul_f32 v[122:123], v[84:85], v[84:85]
	v_add_f32_e32 v8, v127, v8
	v_and_b32_e32 v83, 0xffff0000, v26
	v_lshlrev_b32_e32 v82, 16, v26
	v_add_f32_e32 v8, v122, v8
	v_pk_mul_f32 v[118:119], v[82:83], v[82:83]
	v_add_f32_e32 v8, v123, v8
	v_and_b32_e32 v79, 0xffff0000, v27
	v_lshlrev_b32_e32 v78, 16, v27
	v_add_f32_e32 v8, v118, v8
	v_pk_mul_f32 v[114:115], v[78:79], v[78:79]
	v_add_f32_e32 v8, v119, v8
	v_add_f32_e32 v8, v114, v8
	v_pk_mul_f32 v[40:41], v[74:75], v[74:75]
	v_add_f32_e32 v8, v115, v8
	v_add_f32_e32 v8, v40, v8
	v_pk_mul_f32 v[34:35], v[70:71], v[70:71]
	v_add_f32_e32 v8, v41, v8
	v_add_f32_e32 v8, v34, v8
	v_and_b32_e32 v77, 0xffff0000, v29
	v_lshlrev_b32_e32 v76, 16, v29
	v_and_b32_e32 v81, 0xffff0000, v28
	v_lshlrev_b32_e32 v80, 16, v28
	v_pk_mul_f32 v[28:29], v[66:67], v[66:67]
	v_add_f32_e32 v8, v35, v8
	v_add_f32_e32 v8, v28, v8
	v_pk_mul_f32 v[24:25], v[62:63], v[62:63]
	v_add_f32_e32 v8, v29, v8
	v_add_f32_e32 v8, v24, v8
	v_pk_mul_f32 v[130:131], v[80:81], v[80:81]
	v_add_f32_e32 v8, v25, v8
	v_add_f32_e32 v8, v130, v8
	v_pk_mul_f32 v[124:125], v[76:77], v[76:77]
	v_add_f32_e32 v8, v131, v8
	v_and_b32_e32 v73, 0xffff0000, v30
	v_lshlrev_b32_e32 v72, 16, v30
	v_add_f32_e32 v8, v124, v8
	v_pk_mul_f32 v[120:121], v[72:73], v[72:73]
	v_add_f32_e32 v8, v125, v8
	v_and_b32_e32 v69, 0xffff0000, v31
	v_lshlrev_b32_e32 v68, 16, v31
	v_add_f32_e32 v8, v120, v8
	v_pk_mul_f32 v[116:117], v[68:69], v[68:69]
	v_add_f32_e32 v8, v121, v8
	v_add_f32_e32 v8, v116, v8
	v_pk_mul_f32 v[42:43], v[64:65], v[64:65]
	v_add_f32_e32 v8, v117, v8
	v_add_f32_e32 v8, v42, v8
	v_pk_mul_f32 v[38:39], v[60:61], v[60:61]
	v_add_f32_e32 v8, v43, v8
	v_and_b32_e32 v59, 0xffff0000, v22
	v_lshlrev_b32_e32 v58, 16, v22
	v_add_f32_e32 v8, v38, v8
	v_pk_mul_f32 v[30:31], v[58:59], v[58:59]
	v_add_f32_e32 v8, v39, v8
	v_and_b32_e32 v57, 0xffff0000, v23
	v_lshlrev_b32_e32 v56, 16, v23
	v_add_f32_e32 v8, v30, v8
	v_pk_mul_f32 v[26:27], v[56:57], v[56:57]
	v_add_f32_e32 v8, v31, v8
	v_add_f32_e32 v8, v26, v8
	v_add_f32_e32 v8, v27, v8
	v_fmamk_f32 v8, v8, 0x3c800000, v201
	v_mul_f32_e32 v9, 0x4f800000, v8
	v_cmp_gt_f32_e32 vcc, s6, v8
	global_load_dwordx4 v[16:19], v[48:49], off offset:48
	global_load_dwordx4 v[20:23], v[48:49], off offset:32
	v_cndmask_b32_e32 v24, v8, v9, vcc
	v_sqrt_f32_e32 v25, v24
	global_load_dwordx4 v[8:11], v[48:49], off offset:80
	global_load_dwordx4 v[12:15], v[48:49], off offset:64
	v_add_u32_e32 v26, -1, v25
	v_fma_f32 v27, -v26, v25, v24
	v_cmp_ge_f32_e64 s[40:41], 0, v27
	v_add_u32_e32 v27, 1, v25
	s_nop 0
	v_cndmask_b32_e64 v26, v25, v26, s[40:41]
	v_fma_f32 v25, -v27, v25, v24
	v_cmp_lt_f32_e64 s[40:41], 0, v25
	s_nop 1
	v_cndmask_b32_e64 v25, v26, v27, s[40:41]
	v_mul_f32_e32 v26, 0x37800000, v25
	v_cndmask_b32_e32 v25, v25, v26, vcc
	v_cmp_class_f32_e32 vcc, v24, v202
	s_nop 1
	v_cndmask_b32_e32 v118, v25, v24, vcc
	v_div_scale_f32 v36, s[12:13], v118, v118, 1.0
	v_rcp_f32_e32 v37, v36
	global_load_dwordx4 v[24:27], v[48:49], off offset:96
	global_load_dwordx4 v[32:35], v[48:49], off offset:112
	global_load_dwordx4 v[28:31], v[48:49], off offset:144
	global_load_dwordx4 v[40:43], v[48:49], off offset:128
	v_fma_f32 v38, -v36, v37, 1.0
	v_fmac_f32_e32 v37, v38, v37
	v_div_scale_f32 v38, vcc, 1.0, v118, 1.0
	v_mul_f32_e32 v39, v38, v37
	v_fma_f32 v114, -v36, v39, v38
	v_fmac_f32_e32 v39, v114, v37
	v_fma_f32 v36, -v36, v39, v38
	v_div_fmas_f32 v119, v36, v37, v39
	global_load_dwordx4 v[36:39], v[48:49], off offset:176
	global_load_dwordx4 v[114:117], v[48:49], off offset:160
	v_div_fixup_f32 v126, v119, v118, 1.0
	v_pk_mul_f32 v[112:113], v[126:127], v[112:113] op_sel_hi:[0,1]
	s_waitcnt vmcnt(10)
; __device__ __forceinline__ void phase_prep(const Params& P, int l, unsigned char* lds) {
;     ...
;                 const float rstd = 1.0f / sqrtf(s2 * (1.0f / 64.0f) + RMS_EPS);
; #pragma unroll
;                 for (int j = 0; j < 64; ++j) v[j] = v[j] * rstd * gain[j];
;                 if (!is_ctx) { const int tl = t0 - CTX + tok; rope_half<16>(v, tl >> 6); rope_half<16>(v + 32, tl & 63); }
	v_pk_mul_f32 v[112:113], v[4:5], v[112:113]
	v_pk_mul_f32 v[4:5], v[126:127], v[110:111] op_sel_hi:[0,1]
	v_pk_mul_f32 v[110:111], v[6:7], v[4:5]
	global_load_dwordx4 v[4:7], v[48:49], off offset:192
	v_pk_mul_f32 v[108:109], v[126:127], v[108:109] op_sel_hi:[0,1]
	v_pk_mul_f32 v[108:109], v[0:1], v[108:109]
	v_pk_mul_f32 v[0:1], v[126:127], v[106:107] op_sel_hi:[0,1]
	v_pk_mul_f32 v[106:107], v[2:3], v[0:1]
	global_load_dwordx4 v[0:3], v[48:49], off offset:208
	global_load_dwordx4 v[118:121], v[48:49], off offset:224
	global_load_dwordx4 v[122:125], v[48:49], off offset:240
	v_pk_mul_f32 v[104:105], v[126:127], v[104:105] op_sel_hi:[0,1]
	s_andn2_b64 vcc, exec, s[42:43]
	s_waitcnt vmcnt(12)
	v_pk_mul_f32 v[104:105], v[20:21], v[104:105]
	v_pk_mul_f32 v[20:21], v[126:127], v[102:103] op_sel_hi:[0,1]
	v_pk_mul_f32 v[102:103], v[22:23], v[20:21]
	v_pk_mul_f32 v[20:21], v[126:127], v[98:99] op_sel_hi:[0,1]
	v_pk_mul_f32 v[98:99], v[16:17], v[20:21]
	v_pk_mul_f32 v[16:17], v[126:127], v[92:93] op_sel_hi:[0,1]
	v_pk_mul_f32 v[92:93], v[18:19], v[16:17]
	v_pk_mul_f32 v[16:17], v[126:127], v[54:55] op_sel_hi:[0,1]
	s_waitcnt vmcnt(10)
	v_pk_mul_f32 v[54:55], v[12:13], v[16:17]
	v_pk_mul_f32 v[12:13], v[126:127], v[52:53] op_sel_hi:[0,1]
	v_pk_mul_f32 v[52:53], v[14:15], v[12:13]
	v_pk_mul_f32 v[12:13], v[126:127], v[50:51] op_sel_hi:[0,1]
	v_pk_mul_f32 v[50:51], v[8:9], v[12:13]
	v_pk_mul_f32 v[8:9], v[126:127], v[100:101] op_sel_hi:[0,1]
	v_pk_mul_f32 v[48:49], v[10:11], v[8:9]
	v_pk_mul_f32 v[8:9], v[126:127], v[96:97] op_sel_hi:[0,1]
	s_waitcnt vmcnt(9)
	v_pk_mul_f32 v[22:23], v[24:25], v[8:9]
	v_pk_mul_f32 v[8:9], v[126:127], v[94:95] op_sel_hi:[0,1]
	v_pk_mul_f32 v[20:21], v[26:27], v[8:9]
	v_pk_mul_f32 v[8:9], v[126:127], v[90:91] op_sel_hi:[0,1]
	s_waitcnt vmcnt(8)
	v_pk_mul_f32 v[18:19], v[32:33], v[8:9]
	v_pk_mul_f32 v[8:9], v[126:127], v[88:89] op_sel_hi:[0,1]
	v_pk_mul_f32 v[16:17], v[34:35], v[8:9]
	v_pk_mul_f32 v[8:9], v[126:127], v[86:87] op_sel_hi:[0,1]
	s_waitcnt vmcnt(6)
	v_pk_mul_f32 v[86:87], v[40:41], v[8:9]
	v_pk_mul_f32 v[8:9], v[126:127], v[84:85] op_sel_hi:[0,1]
	v_pk_mul_f32 v[42:43], v[42:43], v[8:9]
	v_pk_mul_f32 v[8:9], v[126:127], v[82:83] op_sel_hi:[0,1]
	v_pk_mul_f32 v[40:41], v[28:29], v[8:9]
	v_pk_mul_f32 v[8:9], v[126:127], v[78:79] op_sel_hi:[0,1]
	v_pk_mul_f32 v[32:33], v[30:31], v[8:9]
	v_pk_mul_f32 v[8:9], v[126:127], v[74:75] op_sel_hi:[0,1]
	s_waitcnt vmcnt(4)
	v_pk_mul_f32 v[30:31], v[114:115], v[8:9]
	v_pk_mul_f32 v[8:9], v[126:127], v[70:71] op_sel_hi:[0,1]
	v_pk_mul_f32 v[28:29], v[116:117], v[8:9]
	v_pk_mul_f32 v[8:9], v[126:127], v[66:67] op_sel_hi:[0,1]
	v_pk_mul_f32 v[26:27], v[36:37], v[8:9]
	v_pk_mul_f32 v[8:9], v[126:127], v[62:63] op_sel_hi:[0,1]
	v_pk_mul_f32 v[24:25], v[38:39], v[8:9]
	v_pk_mul_f32 v[8:9], v[126:127], v[80:81] op_sel_hi:[0,1]
	s_waitcnt vmcnt(3)
	v_pk_mul_f32 v[14:15], v[4:5], v[8:9]
	v_pk_mul_f32 v[4:5], v[126:127], v[76:77] op_sel_hi:[0,1]
	v_pk_mul_f32 v[12:13], v[6:7], v[4:5]
	v_pk_mul_f32 v[4:5], v[126:127], v[72:73] op_sel_hi:[0,1]
	s_waitcnt vmcnt(2)
	v_pk_mul_f32 v[10:11], v[0:1], v[4:5]
	v_pk_mul_f32 v[0:1], v[126:127], v[68:69] op_sel_hi:[0,1]
	v_pk_mul_f32 v[8:9], v[2:3], v[0:1]
	v_pk_mul_f32 v[0:1], v[126:127], v[64:65] op_sel_hi:[0,1]
	s_waitcnt vmcnt(1)
	v_pk_mul_f32 v[4:5], v[118:119], v[0:1]
	v_pk_mul_f32 v[0:1], v[126:127], v[60:61] op_sel_hi:[0,1]
	v_pk_mul_f32 v[2:3], v[120:121], v[0:1]
	v_pk_mul_f32 v[0:1], v[126:127], v[58:59] op_sel_hi:[0,1]
	v_pk_mul_f32 v[6:7], v[126:127], v[56:57] op_sel_hi:[0,1]
	s_waitcnt vmcnt(0)
	v_pk_mul_f32 v[0:1], v[122:123], v[0:1]
	v_pk_mul_f32 v[6:7], v[124:125], v[6:7]
	s_cbranch_vccnz .LBB0_287
	v_add_u32_e32 v45, s15, v45
	v_ashrrev_i32_e32 v34, 6, v45
	v_cvt_f32_i32_e32 v69, v34
	v_and_b32_e32 v45, 63, v45
	v_cvt_f32_ubyte0_e32 v45, v45
	v_mul_f32_e32 v34, 0.15915494, v69
	v_cos_f32_e32 v36, v34
	v_sin_f32_e32 v38, v34
	v_mul_f32_e32 v34, 0x3f0ff59a, v69
	v_mul_f32_e32 v34, 0.15915494, v34
	v_sin_f32_e32 v39, v34
	v_cos_f32_e32 v37, v34
	v_pk_mul_f32 v[34:35], v[38:39], v[54:55]
	s_nop 0
	v_pk_fma_f32 v[34:35], v[36:37], v[112:113], v[34:35] neg_lo:[0,0,1] neg_hi:[0,0,1]
	v_pk_mul_f32 v[36:37], v[36:37], v[54:55]
	s_nop 0
	v_pk_fma_f32 v[54:55], v[38:39], v[112:113], v[36:37]
	v_mul_f32_e32 v36, 0x3ea1e89b, v69
	v_mul_f32_e32 v36, 0.15915494, v36
	v_cos_f32_e32 v38, v36
	v_sin_f32_e32 v56, v36
	v_mul_f32_e32 v36, 0x3e361888, v69
	v_mul_f32_e32 v36, 0.15915494, v36
	v_sin_f32_e32 v57, v36
	v_cos_f32_e32 v39, v36
	v_mov_b64_e32 v[112:113], v[34:35]
	v_pk_mul_f32 v[36:37], v[56:57], v[52:53]
	s_nop 0
	v_pk_fma_f32 v[36:37], v[38:39], v[110:111], v[36:37] neg_lo:[0,0,1] neg_hi:[0,0,1]
	v_pk_mul_f32 v[38:39], v[38:39], v[52:53]
	s_nop 0
	v_pk_fma_f32 v[52:53], v[56:57], v[110:111], v[38:39]
	v_mul_f32_e32 v38, 0x3dcccccd, v69
	v_mul_f32_e32 v38, 0.15915494, v38
	v_cos_f32_e32 v56, v38
	v_sin_f32_e32 v58, v38
	v_mul_f32_e32 v38, 0x3d6655c4, v69
	v_mul_f32_e32 v38, 0.15915494, v38
	v_sin_f32_e32 v59, v38
	v_cos_f32_e32 v57, v38
	v_mov_b64_e32 v[110:111], v[36:37]
	v_pk_mul_f32 v[38:39], v[58:59], v[50:51]
	s_nop 0
	v_pk_fma_f32 v[38:39], v[56:57], v[108:109], v[38:39] neg_lo:[0,0,1] neg_hi:[0,0,1]
	v_pk_mul_f32 v[50:51], v[56:57], v[50:51]
	v_mul_f32_e32 v56, 0x3d0186e3, v69
	v_mul_f32_e32 v56, 0.15915494, v56
	v_pk_fma_f32 v[50:51], v[58:59], v[108:109], v[50:51]
	v_cos_f32_e32 v58, v56
	v_sin_f32_e32 v60, v56
	v_mul_f32_e32 v56, 0x3c91ad3a, v69
	v_mul_f32_e32 v56, 0.15915494, v56
	v_sin_f32_e32 v61, v56
	v_cos_f32_e32 v59, v56
	v_mov_b64_e32 v[108:109], v[38:39]
	v_pk_mul_f32 v[56:57], v[60:61], v[48:49]
	s_nop 0
; template <int NF> __device__ __forceinline__ void rope_half(float* v, int pos) {
; #pragma unroll
;     for (int i = 0; i < NF; ++i) {
;         const float inv_freq = exp2f(-13.287712379549449f * (float)i / (float)NF);
;         const float rev = (float)pos * inv_freq * 0.15915494309189535f;
;         const float cs = __builtin_amdgcn_cosf(rev), sn = __builtin_amdgcn_sinf(rev);
;         const float x1 = v[i], x2 = v[NF + i];
;         v[i] = x1 * cs - x2 * sn; v[NF + i] = x2 * cs + x1 * sn;
;     }
	v_pk_fma_f32 v[56:57], v[58:59], v[106:107], v[56:57] neg_lo:[0,0,1] neg_hi:[0,0,1]
	v_pk_mul_f32 v[48:49], v[58:59], v[48:49]
	v_mul_f32_e32 v58, 0x3c23d70b, v69
	v_mul_f32_e32 v58, 0.15915494, v58
	v_pk_fma_f32 v[48:49], v[60:61], v[106:107], v[48:49]
	v_cos_f32_e32 v60, v58
	v_sin_f32_e32 v62, v58
	v_mul_f32_e32 v58, 0x3bb8449d, v69
	v_mul_f32_e32 v58, 0.15915494, v58
	v_sin_f32_e32 v63, v58
	v_cos_f32_e32 v61, v58
	v_mov_b64_e32 v[106:107], v[56:57]
	v_pk_mul_f32 v[58:59], v[62:63], v[22:23]
	s_nop 0
	v_pk_fma_f32 v[58:59], v[60:61], v[104:105], v[58:59] neg_lo:[0,0,1] neg_hi:[0,0,1]
	v_pk_mul_f32 v[22:23], v[60:61], v[22:23]
	v_mul_f32_e32 v60, 0x3b4f3e39, v69
	v_mul_f32_e32 v60, 0.15915494, v60
	v_pk_fma_f32 v[22:23], v[62:63], v[104:105], v[22:23]
	v_cos_f32_e32 v62, v60
	v_sin_f32_e32 v64, v60
	v_mul_f32_e32 v60, 0x3ae9152f, v69
	v_mul_f32_e32 v60, 0.15915494, v60
	v_sin_f32_e32 v65, v60
	v_cos_f32_e32 v63, v60
	v_mov_b64_e32 v[104:105], v[58:59]
	v_pk_mul_f32 v[60:61], v[64:65], v[20:21]
	s_nop 0
	v_pk_fma_f32 v[60:61], v[62:63], v[102:103], v[60:61] neg_lo:[0,0,1] neg_hi:[0,0,1]
	v_pk_mul_f32 v[20:21], v[62:63], v[20:21]
	v_mul_f32_e32 v62, 0x3a831270, v69
	v_mul_f32_e32 v62, 0.15915494, v62
	v_pk_fma_f32 v[20:21], v[64:65], v[102:103], v[20:21]
	v_cos_f32_e32 v64, v62
	v_sin_f32_e32 v66, v62
	v_mul_f32_e32 v62, 0x3a136a15, v69
	v_mul_f32_e32 v62, 0.15915494, v62
	v_sin_f32_e32 v67, v62
	v_cos_f32_e32 v65, v62
	v_mov_b64_e32 v[102:103], v[60:61]
	v_pk_mul_f32 v[62:63], v[66:67], v[18:19]
	s_nop 0
	v_pk_fma_f32 v[62:63], v[64:65], v[98:99], v[62:63] neg_lo:[0,0,1] neg_hi:[0,0,1]
	v_pk_mul_f32 v[18:19], v[64:65], v[18:19]
	v_mul_f32_e32 v64, 0x39a5cb61, v69
	v_mul_f32_e32 v64, 0.15915494, v64
	v_pk_fma_f32 v[18:19], v[66:67], v[98:99], v[18:19]
	v_cos_f32_e32 v66, v64
	v_sin_f32_e32 v68, v64
	v_mul_f32_e32 v64, 0x393a7759, v69
	v_mul_f32_e32 v64, 0.15915494, v64
	v_sin_f32_e32 v69, v64
	v_cos_f32_e32 v67, v64
	v_mov_b64_e32 v[98:99], v[62:63]
	v_pk_mul_f32 v[64:65], v[68:69], v[16:17]
	s_nop 0
	v_pk_fma_f32 v[64:65], v[66:67], v[92:93], v[64:65] neg_lo:[0,0,1] neg_hi:[0,0,1]
	v_pk_mul_f32 v[16:17], v[66:67], v[16:17]
	v_mul_f32_e32 v66, 0.15915494, v45
	v_pk_fma_f32 v[16:17], v[68:69], v[92:93], v[16:17]
	v_cos_f32_e32 v68, v66
	v_sin_f32_e32 v70, v66
	v_mul_f32_e32 v66, 0x3f0ff59a, v45
	v_mul_f32_e32 v66, 0.15915494, v66
	v_sin_f32_e32 v71, v66
	v_cos_f32_e32 v69, v66
	v_mov_b64_e32 v[92:93], v[64:65]
	v_pk_mul_f32 v[66:67], v[70:71], v[14:15]
	s_nop 0
	v_pk_fma_f32 v[66:67], v[68:69], v[86:87], v[66:67] neg_lo:[0,0,1] neg_hi:[0,0,1]
	v_pk_mul_f32 v[14:15], v[68:69], v[14:15]
	v_mul_f32_e32 v68, 0x3ea1e89b, v45
	v_mul_f32_e32 v68, 0.15915494, v68
	v_pk_fma_f32 v[14:15], v[70:71], v[86:87], v[14:15]
	v_cos_f32_e32 v70, v68
	v_sin_f32_e32 v72, v68
	v_mul_f32_e32 v68, 0x3e361888, v45
	v_mul_f32_e32 v68, 0.15915494, v68
	v_cos_f32_e32 v71, v68
	v_sin_f32_e32 v73, v68
	v_mov_b64_e32 v[86:87], v[66:67]
	v_pk_mul_f32 v[68:69], v[72:73], v[12:13]
	v_pk_mul_f32 v[12:13], v[70:71], v[12:13]
	v_pk_fma_f32 v[68:69], v[70:71], v[42:43], v[68:69] neg_lo:[0,0,1] neg_hi:[0,0,1]
	v_pk_fma_f32 v[12:13], v[72:73], v[42:43], v[12:13]
	v_mul_f32_e32 v42, 0x3dcccccd, v45
	v_mul_f32_e32 v43, 0.15915494, v42
	v_cos_f32_e32 v42, v43
	v_sin_f32_e32 v70, v43
	v_mul_f32_e32 v43, 0x3d6655c4, v45
	v_mul_f32_e32 v71, 0.15915494, v43
	v_cos_f32_e32 v43, v71
	v_sin_f32_e32 v71, v71
	s_nop 0
	v_pk_mul_f32 v[72:73], v[70:71], v[10:11]
	v_pk_mul_f32 v[10:11], v[42:43], v[10:11]
	v_pk_fma_f32 v[72:73], v[42:43], v[40:41], v[72:73] neg_lo:[0,0,1] neg_hi:[0,0,1]
	v_pk_fma_f32 v[10:11], v[70:71], v[40:41], v[10:11]
	v_mul_f32_e32 v40, 0x3d0186e3, v45
	v_mul_f32_e32 v41, 0.15915494, v40
	v_cos_f32_e32 v40, v41
	v_sin_f32_e32 v42, v41
	v_mul_f32_e32 v41, 0x3c91ad3a, v45
	v_mul_f32_e32 v43, 0.15915494, v41
	v_cos_f32_e32 v41, v43
	v_sin_f32_e32 v43, v43
	s_nop 0
	v_pk_mul_f32 v[70:71], v[42:43], v[8:9]
	v_pk_mul_f32 v[8:9], v[40:41], v[8:9]
	v_pk_fma_f32 v[70:71], v[40:41], v[32:33], v[70:71] neg_lo:[0,0,1] neg_hi:[0,0,1]
	v_pk_fma_f32 v[8:9], v[42:43], v[32:33], v[8:9]
	v_mul_f32_e32 v32, 0x3c23d70b, v45
	v_mul_f32_e32 v33, 0.15915494, v32
	v_cos_f32_e32 v32, v33
	v_sin_f32_e32 v40, v33
	v_mul_f32_e32 v33, 0x3bb8449d, v45
	v_mul_f32_e32 v41, 0.15915494, v33
	v_cos_f32_e32 v33, v41
	v_sin_f32_e32 v41, v41
	s_nop 0
	v_pk_mul_f32 v[42:43], v[40:41], v[4:5]
	v_pk_mul_f32 v[4:5], v[32:33], v[4:5]
	v_pk_fma_f32 v[42:43], v[32:33], v[30:31], v[42:43] neg_lo:[0,0,1] neg_hi:[0,0,1]
	v_pk_fma_f32 v[4:5], v[40:41], v[30:31], v[4:5]
	v_mul_f32_e32 v30, 0x3b4f3e39, v45
	v_mul_f32_e32 v31, 0.15915494, v30
	v_cos_f32_e32 v30, v31
	v_sin_f32_e32 v32, v31
	v_mul_f32_e32 v31, 0x3ae9152f, v45
	v_mul_f32_e32 v33, 0.15915494, v31
	v_cos_f32_e32 v31, v33
	v_sin_f32_e32 v33, v33
	s_nop 0
	v_pk_mul_f32 v[40:41], v[32:33], v[2:3]
	v_pk_mul_f32 v[2:3], v[30:31], v[2:3]
	v_pk_fma_f32 v[40:41], v[30:31], v[28:29], v[40:41] neg_lo:[0,0,1] neg_hi:[0,0,1]
	v_pk_fma_f32 v[2:3], v[32:33], v[28:29], v[2:3]
	v_mul_f32_e32 v28, 0x3a831270, v45
	v_mul_f32_e32 v29, 0.15915494, v28
	v_cos_f32_e32 v28, v29
	v_sin_f32_e32 v30, v29
	v_mul_f32_e32 v29, 0x3a136a15, v45
	v_mul_f32_e32 v31, 0.15915494, v29
	v_cos_f32_e32 v29, v31
	v_sin_f32_e32 v31, v31
	s_nop 0
	v_pk_mul_f32 v[32:33], v[30:31], v[0:1]
	v_pk_mul_f32 v[0:1], v[28:29], v[0:1]
	v_pk_fma_f32 v[32:33], v[28:29], v[26:27], v[32:33] neg_lo:[0,0,1] neg_hi:[0,0,1]
	v_pk_fma_f32 v[0:1], v[30:31], v[26:27], v[0:1]
	v_mul_f32_e32 v26, 0x39a5cb61, v45
	v_mul_f32_e32 v27, 0.15915494, v26
	v_cos_f32_e32 v26, v27
	v_sin_f32_e32 v28, v27
	v_mul_f32_e32 v27, 0x393a7759, v45
	v_mul_f32_e32 v29, 0.15915494, v27
	v_cos_f32_e32 v27, v29
	v_sin_f32_e32 v29, v29
	s_nop 0
	v_pk_mul_f32 v[30:31], v[28:29], v[6:7]
	s_nop 0
	v_pk_fma_f32 v[30:31], v[26:27], v[24:25], v[30:31] neg_lo:[0,0,1] neg_hi:[0,0,1]
	v_pk_mul_f32 v[6:7], v[26:27], v[6:7]
	v_mov_b64_e32 v[26:27], v[32:33]
	v_pk_fma_f32 v[6:7], v[28:29], v[24:25], v[6:7]
	v_mov_b64_e32 v[24:25], v[30:31]
	v_mov_b64_e32 v[28:29], v[40:41]
	v_mov_b64_e32 v[30:31], v[42:43]
	v_mov_b64_e32 v[32:33], v[70:71]
	v_mov_b64_e32 v[40:41], v[72:73]
	v_mov_b64_e32 v[42:43], v[68:69]
